# fast loop variant: zero softmax shift (scores unshifted, SrcC=0 on the first QK k-step), exit screen also bounds l from below; exact rerun fallback unchanged
# baseline (speedup 1.0000x reference)
.Lat_floop:
	s_waitcnt lgkmcnt(0)
	v_mfma_f32_32x32x16_bf16 v[96:111], v[48:51], v[136:139], 0
	ds_read_b64_tr_b16 v[168:169], v146 offset:0
	ds_read_b64_tr_b16 v[170:171], v146 offset:1024
	ds_read_b64_tr_b16 v[172:173], v146 offset:512
	ds_read_b64_tr_b16 v[174:175], v146 offset:1536
	v_mfma_f32_32x32x16_bf16 v[96:111], v[52:55], v[140:143], v[96:111]
	ds_read_b64_tr_b16 v[176:177], v146 offset:2048
	ds_read_b64_tr_b16 v[178:179], v146 offset:3072
	ds_read_b64_tr_b16 v[180:181], v146 offset:2560
	ds_read_b64_tr_b16 v[182:183], v146 offset:3584
	v_mfma_f32_32x32x16_bf16 v[112:127], v[56:59], v[136:139], 0
	ds_read_b64_tr_b16 v[184:185], v146 offset:4096
	ds_read_b64_tr_b16 v[186:187], v146 offset:5120
	ds_read_b64_tr_b16 v[188:189], v146 offset:4608
	ds_read_b64_tr_b16 v[190:191], v146 offset:5632
	v_mfma_f32_32x32x16_bf16 v[112:127], v[60:63], v[140:143], v[112:127]
	ds_read_b64_tr_b16 v[192:193], v146 offset:6144
	ds_read_b64_tr_b16 v[194:195], v146 offset:7168
	ds_read_b64_tr_b16 v[196:197], v146 offset:6656
	ds_read_b64_tr_b16 v[198:199], v146 offset:7680
	v_exp_f32_e32 v96, v96
	v_exp_f32_e32 v97, v97
	v_exp_f32_e32 v98, v98
	v_exp_f32_e32 v99, v99
	v_exp_f32_e32 v100, v100
	v_exp_f32_e32 v101, v101
	v_exp_f32_e32 v102, v102
	v_exp_f32_e32 v103, v103
	v_cvt_pk_bf16_f32 v162, v96, v97
	v_cvt_pk_bf16_f32 v163, v98, v99
	v_cvt_pk_bf16_f32 v164, v100, v101
	v_cvt_pk_bf16_f32 v165, v102, v103
	v_pk_add_f32 v[128:129], v[128:129], v[96:97]
	v_pk_add_f32 v[128:129], v[128:129], v[98:99]
	v_pk_add_f32 v[128:129], v[128:129], v[100:101]
	v_pk_add_f32 v[128:129], v[128:129], v[102:103]
	s_waitcnt lgkmcnt(12)
	v_mfma_f32_32x32x16_bf16 v[0:15], v[162:165], v[168:171], v[0:15]
	v_exp_f32_e32 v104, v104
	v_exp_f32_e32 v105, v105
	v_exp_f32_e32 v106, v106
	v_exp_f32_e32 v107, v107
	v_mfma_f32_32x32x16_bf16 v[16:31], v[162:165], v[172:175], v[16:31]
	v_exp_f32_e32 v108, v108
	v_exp_f32_e32 v109, v109
	v_exp_f32_e32 v110, v110
	v_exp_f32_e32 v111, v111
	v_cvt_pk_bf16_f32 v162, v104, v105
	v_cvt_pk_bf16_f32 v163, v106, v107
	v_cvt_pk_bf16_f32 v164, v108, v109
	v_cvt_pk_bf16_f32 v165, v110, v111
	v_pk_add_f32 v[128:129], v[128:129], v[104:105]
	v_pk_add_f32 v[128:129], v[128:129], v[106:107]
	v_pk_add_f32 v[128:129], v[128:129], v[108:109]
	v_pk_add_f32 v[128:129], v[128:129], v[110:111]
	s_waitcnt lgkmcnt(8)
	v_mfma_f32_32x32x16_bf16 v[0:15], v[162:165], v[176:179], v[0:15]
	v_exp_f32_e32 v112, v112
	v_exp_f32_e32 v113, v113
	v_exp_f32_e32 v114, v114
	v_exp_f32_e32 v115, v115
	v_mfma_f32_32x32x16_bf16 v[16:31], v[162:165], v[180:183], v[16:31]
	v_mfma_f32_32x32x16_bf16 v[96:111], v[48:51], v[150:153], 0
	v_exp_f32_e32 v116, v116
	v_exp_f32_e32 v117, v117
	v_exp_f32_e32 v118, v118
	v_exp_f32_e32 v119, v119
	v_mfma_f32_32x32x16_bf16 v[96:111], v[52:55], v[154:157], v[96:111]
	v_cvt_pk_bf16_f32 v162, v112, v113
	v_cvt_pk_bf16_f32 v163, v114, v115
	v_cvt_pk_bf16_f32 v164, v116, v117
	v_cvt_pk_bf16_f32 v165, v118, v119
	v_pk_add_f32 v[128:129], v[128:129], v[112:113]
	v_pk_add_f32 v[128:129], v[128:129], v[114:115]
	v_pk_add_f32 v[128:129], v[128:129], v[116:117]
	v_pk_add_f32 v[128:129], v[128:129], v[118:119]
	s_waitcnt lgkmcnt(4)
	v_mfma_f32_32x32x16_bf16 v[0:15], v[162:165], v[184:187], v[0:15]
	v_exp_f32_e32 v120, v120
	v_exp_f32_e32 v121, v121
	v_exp_f32_e32 v122, v122
	v_exp_f32_e32 v123, v123
	v_mfma_f32_32x32x16_bf16 v[16:31], v[162:165], v[188:191], v[16:31]
	v_exp_f32_e32 v124, v124
	v_exp_f32_e32 v125, v125
	v_exp_f32_e32 v126, v126
	v_exp_f32_e32 v127, v127
	v_cvt_pk_bf16_f32 v162, v120, v121
	v_cvt_pk_bf16_f32 v163, v122, v123
	v_cvt_pk_bf16_f32 v164, v124, v125
	v_cvt_pk_bf16_f32 v165, v126, v127
	v_pk_add_f32 v[128:129], v[128:129], v[120:121]
	v_pk_add_f32 v[128:129], v[128:129], v[122:123]
	v_pk_add_f32 v[128:129], v[128:129], v[124:125]
	v_pk_add_f32 v[128:129], v[128:129], v[126:127]
	v_mfma_f32_32x32x16_bf16 v[112:127], v[56:59], v[150:153], 0
	v_mfma_f32_32x32x16_bf16 v[112:127], v[60:63], v[154:157], v[112:127]
	s_waitcnt lgkmcnt(0)
	v_mfma_f32_32x32x16_bf16 v[0:15], v[162:165], v[192:195], v[0:15]
	v_mfma_f32_32x32x16_bf16 v[16:31], v[162:165], v[196:199], v[16:31]
	ds_read_b128 v[48:51], v144 offset:8192
	ds_read_b128 v[52:55], v145 offset:8192
	ds_read_b128 v[56:59], v144 offset:12288
	ds_read_b128 v[60:63], v145 offset:12288
	v_exp_f32_e32 v96, v96
	v_exp_f32_e32 v97, v97
	v_exp_f32_e32 v98, v98
	v_exp_f32_e32 v99, v99
	v_exp_f32_e32 v100, v100
	v_exp_f32_e32 v101, v101
	v_exp_f32_e32 v102, v102
	v_exp_f32_e32 v103, v103
	v_cvt_pk_bf16_f32 v162, v96, v97
	v_cvt_pk_bf16_f32 v163, v98, v99
	v_cvt_pk_bf16_f32 v164, v100, v101
	v_cvt_pk_bf16_f32 v165, v102, v103
	v_pk_add_f32 v[130:131], v[130:131], v[96:97]
	v_pk_add_f32 v[130:131], v[130:131], v[98:99]
	v_pk_add_f32 v[130:131], v[130:131], v[100:101]
	v_pk_add_f32 v[130:131], v[130:131], v[102:103]
	v_mfma_f32_32x32x16_bf16 v[80:95], v[162:165], v[168:171], v[80:95]
	v_exp_f32_e32 v104, v104
	v_exp_f32_e32 v105, v105
	v_exp_f32_e32 v106, v106
	v_exp_f32_e32 v107, v107
	v_mfma_f32_32x32x16_bf16 v[200:215], v[162:165], v[172:175], v[200:215]
	v_exp_f32_e32 v108, v108
	v_exp_f32_e32 v109, v109
	v_exp_f32_e32 v110, v110
	v_exp_f32_e32 v111, v111
	v_cvt_pk_bf16_f32 v162, v104, v105
	v_cvt_pk_bf16_f32 v163, v106, v107
	v_cvt_pk_bf16_f32 v164, v108, v109
	v_cvt_pk_bf16_f32 v165, v110, v111
	v_pk_add_f32 v[130:131], v[130:131], v[104:105]
	v_pk_add_f32 v[130:131], v[130:131], v[106:107]
	v_pk_add_f32 v[130:131], v[130:131], v[108:109]
	v_pk_add_f32 v[130:131], v[130:131], v[110:111]
	v_mfma_f32_32x32x16_bf16 v[80:95], v[162:165], v[176:179], v[80:95]
	v_exp_f32_e32 v112, v112
	v_exp_f32_e32 v113, v113
	v_exp_f32_e32 v114, v114
	v_exp_f32_e32 v115, v115
	v_mfma_f32_32x32x16_bf16 v[200:215], v[162:165], v[180:183], v[200:215]
	v_exp_f32_e32 v116, v116
	v_exp_f32_e32 v117, v117
	v_exp_f32_e32 v118, v118
	v_exp_f32_e32 v119, v119
	v_cvt_pk_bf16_f32 v162, v112, v113
	v_cvt_pk_bf16_f32 v163, v114, v115
	v_cvt_pk_bf16_f32 v164, v116, v117
	v_cvt_pk_bf16_f32 v165, v118, v119
	v_pk_add_f32 v[130:131], v[130:131], v[112:113]
	v_pk_add_f32 v[130:131], v[130:131], v[114:115]
	v_pk_add_f32 v[130:131], v[130:131], v[116:117]
	v_pk_add_f32 v[130:131], v[130:131], v[118:119]
	v_mfma_f32_32x32x16_bf16 v[80:95], v[162:165], v[184:187], v[80:95]
	v_exp_f32_e32 v120, v120
	v_exp_f32_e32 v121, v121
	v_exp_f32_e32 v122, v122
	v_exp_f32_e32 v123, v123
	v_mfma_f32_32x32x16_bf16 v[200:215], v[162:165], v[188:191], v[200:215]
	v_exp_f32_e32 v124, v124
	v_exp_f32_e32 v125, v125
	v_exp_f32_e32 v126, v126
	v_exp_f32_e32 v127, v127
	v_cvt_pk_bf16_f32 v162, v120, v121
	v_cvt_pk_bf16_f32 v163, v122, v123
	v_cvt_pk_bf16_f32 v164, v124, v125
	v_cvt_pk_bf16_f32 v165, v126, v127
	v_pk_add_f32 v[130:131], v[130:131], v[120:121]
	v_pk_add_f32 v[130:131], v[130:131], v[122:123]
	v_pk_add_f32 v[130:131], v[130:131], v[124:125]
	v_pk_add_f32 v[130:131], v[130:131], v[126:127]
	v_mfma_f32_32x32x16_bf16 v[80:95], v[162:165], v[192:195], v[80:95]
	v_mfma_f32_32x32x16_bf16 v[200:215], v[162:165], v[196:199], v[200:215]
	s_waitcnt lgkmcnt(0)
	v_mfma_f32_32x32x16_bf16 v[96:111], v[48:51], v[136:139], 0
	ds_read_b64_tr_b16 v[168:169], v146 offset:8192
	ds_read_b64_tr_b16 v[170:171], v146 offset:9216
	ds_read_b64_tr_b16 v[172:173], v146 offset:8704
	ds_read_b64_tr_b16 v[174:175], v146 offset:9728
	v_mfma_f32_32x32x16_bf16 v[96:111], v[52:55], v[140:143], v[96:111]
	ds_read_b64_tr_b16 v[176:177], v146 offset:10240
	ds_read_b64_tr_b16 v[178:179], v146 offset:11264
	ds_read_b64_tr_b16 v[180:181], v146 offset:10752
	ds_read_b64_tr_b16 v[182:183], v146 offset:11776
	v_mfma_f32_32x32x16_bf16 v[112:127], v[56:59], v[136:139], 0
	ds_read_b64_tr_b16 v[184:185], v146 offset:12288
	ds_read_b64_tr_b16 v[186:187], v146 offset:13312
	ds_read_b64_tr_b16 v[188:189], v146 offset:12800
	ds_read_b64_tr_b16 v[190:191], v146 offset:13824
	v_mfma_f32_32x32x16_bf16 v[112:127], v[60:63], v[140:143], v[112:127]
	ds_read_b64_tr_b16 v[192:193], v146 offset:14336
	ds_read_b64_tr_b16 v[194:195], v146 offset:15360
	ds_read_b64_tr_b16 v[196:197], v146 offset:14848
	ds_read_b64_tr_b16 v[198:199], v146 offset:15872
	v_exp_f32_e32 v96, v96
	v_exp_f32_e32 v97, v97
	v_exp_f32_e32 v98, v98
	v_exp_f32_e32 v99, v99
	v_exp_f32_e32 v100, v100
	v_exp_f32_e32 v101, v101
	v_exp_f32_e32 v102, v102
	v_exp_f32_e32 v103, v103
	v_cvt_pk_bf16_f32 v162, v96, v97
	v_cvt_pk_bf16_f32 v163, v98, v99
	v_cvt_pk_bf16_f32 v164, v100, v101
	v_cvt_pk_bf16_f32 v165, v102, v103
	v_pk_add_f32 v[128:129], v[128:129], v[96:97]
	v_pk_add_f32 v[128:129], v[128:129], v[98:99]
	v_pk_add_f32 v[128:129], v[128:129], v[100:101]
	v_pk_add_f32 v[128:129], v[128:129], v[102:103]
	s_waitcnt lgkmcnt(12)
	v_mfma_f32_32x32x16_bf16 v[0:15], v[162:165], v[168:171], v[0:15]
	v_exp_f32_e32 v104, v104
	v_exp_f32_e32 v105, v105
	v_exp_f32_e32 v106, v106
	v_exp_f32_e32 v107, v107
	v_mfma_f32_32x32x16_bf16 v[16:31], v[162:165], v[172:175], v[16:31]
	v_exp_f32_e32 v108, v108
	v_exp_f32_e32 v109, v109
	v_exp_f32_e32 v110, v110
	v_exp_f32_e32 v111, v111
	v_cvt_pk_bf16_f32 v162, v104, v105
	v_cvt_pk_bf16_f32 v163, v106, v107
	v_cvt_pk_bf16_f32 v164, v108, v109
	v_cvt_pk_bf16_f32 v165, v110, v111
	v_pk_add_f32 v[128:129], v[128:129], v[104:105]
	v_pk_add_f32 v[128:129], v[128:129], v[106:107]
	v_pk_add_f32 v[128:129], v[128:129], v[108:109]
	v_pk_add_f32 v[128:129], v[128:129], v[110:111]
	s_waitcnt lgkmcnt(8)
	v_mfma_f32_32x32x16_bf16 v[0:15], v[162:165], v[176:179], v[0:15]
	v_exp_f32_e32 v112, v112
	v_exp_f32_e32 v113, v113
	v_exp_f32_e32 v114, v114
	v_exp_f32_e32 v115, v115
	v_mfma_f32_32x32x16_bf16 v[16:31], v[162:165], v[180:183], v[16:31]
	v_mfma_f32_32x32x16_bf16 v[96:111], v[48:51], v[150:153], 0
	v_exp_f32_e32 v116, v116
	v_exp_f32_e32 v117, v117
	v_exp_f32_e32 v118, v118
	v_exp_f32_e32 v119, v119
	v_mfma_f32_32x32x16_bf16 v[96:111], v[52:55], v[154:157], v[96:111]
	v_cvt_pk_bf16_f32 v162, v112, v113
	v_cvt_pk_bf16_f32 v163, v114, v115
	v_cvt_pk_bf16_f32 v164, v116, v117
	v_cvt_pk_bf16_f32 v165, v118, v119
	v_pk_add_f32 v[128:129], v[128:129], v[112:113]
	v_pk_add_f32 v[128:129], v[128:129], v[114:115]
	v_pk_add_f32 v[128:129], v[128:129], v[116:117]
	v_pk_add_f32 v[128:129], v[128:129], v[118:119]
	s_waitcnt lgkmcnt(4)
	v_mfma_f32_32x32x16_bf16 v[0:15], v[162:165], v[184:187], v[0:15]
	v_exp_f32_e32 v120, v120
	v_exp_f32_e32 v121, v121
	v_exp_f32_e32 v122, v122
	v_exp_f32_e32 v123, v123
	v_mfma_f32_32x32x16_bf16 v[16:31], v[162:165], v[188:191], v[16:31]
	v_exp_f32_e32 v124, v124
	v_exp_f32_e32 v125, v125
	v_exp_f32_e32 v126, v126
	v_exp_f32_e32 v127, v127
	v_cvt_pk_bf16_f32 v162, v120, v121
	v_cvt_pk_bf16_f32 v163, v122, v123
	v_cvt_pk_bf16_f32 v164, v124, v125
	v_cvt_pk_bf16_f32 v165, v126, v127
	v_pk_add_f32 v[128:129], v[128:129], v[120:121]
	v_pk_add_f32 v[128:129], v[128:129], v[122:123]
	v_pk_add_f32 v[128:129], v[128:129], v[124:125]
	v_pk_add_f32 v[128:129], v[128:129], v[126:127]
	v_mfma_f32_32x32x16_bf16 v[112:127], v[56:59], v[150:153], 0
	v_mfma_f32_32x32x16_bf16 v[112:127], v[60:63], v[154:157], v[112:127]
	s_waitcnt lgkmcnt(0)
; #define AT_LOAD(K0, K1, V0, V1, T) do { const size_t e_ = (size_t)(128 * (T) + sr) * 64 + sc; \
;         K0 = *(const bf16x8*)(kcp + e_); V0 = *(const bf16x8*)(vcp + e_); K1 = *(const bf16x8*)(kcp + e_ + 64 * 64); V1 = *(const bf16x8*)(vcp + e_ + 64 * 64); } while (0)
; #define AT_STORE(K0, K1, V0, V1, BUF) do { *(LAS bf16x8*)(lds + AT_K + (BUF) * AT_KB + kst0) = K0; *(LAS bf16x8*)(lds + AT_K + (BUF) * AT_KB + kst1) = K1; \
;         *(LAS bf16x8*)(lds + AT_V + (BUF) * AT_VB + vst0) = V0; *(LAS bf16x8*)(lds + AT_V + (BUF) * AT_VB + vst1) = V1; } while (0)
; template <int VAR>
; __device__ __forceinline__ void attn_unit(const Args& a, int l, int b, int h, int qrow0  , bool ctxu, const bf16* Z, bf16* Y, LAS unsigned char* lds) {
;     ...
;     for (int t = 0; t < NT; t += 2) {
;         __syncthreads();
;         if (t + 2 < NT) AT_LOAD(ka0, ka1, va0, va1, t + 2);
;         attn_tile(Kb0, vb0, q0, q1, negm, m, o0, o1, lacc, t == 0, wsf, r32, hi);
;         AT_STORE(kb0, kb1, vb0_, vb1_, 1);
;         __syncthreads();
;         if (t + 3 < NT) AT_LOAD(kb0, kb1, vb0_, vb1_, t + 3);
;         attn_tile(Kb0 + AT_KB, vb0 + AT_VB, q0, q1, negm, m, o0, o1, lacc, false, wsf, r32, hi);
;         if (t + 2 < NT) AT_STORE(ka0, ka1, va0, va1, 0);
	v_mfma_f32_32x32x16_bf16 v[0:15], v[162:165], v[192:195], v[0:15]
	v_mfma_f32_32x32x16_bf16 v[16:31], v[162:165], v[196:199], v[16:31]
	v_exp_f32_e32 v96, v96
	v_exp_f32_e32 v97, v97
	v_exp_f32_e32 v98, v98
	v_exp_f32_e32 v99, v99
	v_exp_f32_e32 v100, v100
	v_exp_f32_e32 v101, v101
	v_exp_f32_e32 v102, v102
	v_exp_f32_e32 v103, v103
	v_cvt_pk_bf16_f32 v162, v96, v97
	v_cvt_pk_bf16_f32 v163, v98, v99
	v_cvt_pk_bf16_f32 v164, v100, v101
	v_cvt_pk_bf16_f32 v165, v102, v103
	v_pk_add_f32 v[130:131], v[130:131], v[96:97]
	v_pk_add_f32 v[130:131], v[130:131], v[98:99]
	v_pk_add_f32 v[130:131], v[130:131], v[100:101]
	v_pk_add_f32 v[130:131], v[130:131], v[102:103]
	v_mfma_f32_32x32x16_bf16 v[80:95], v[162:165], v[168:171], v[80:95]
	v_exp_f32_e32 v104, v104
	v_exp_f32_e32 v105, v105
	v_exp_f32_e32 v106, v106
	v_exp_f32_e32 v107, v107
	v_mfma_f32_32x32x16_bf16 v[200:215], v[162:165], v[172:175], v[200:215]
	v_exp_f32_e32 v108, v108
	v_exp_f32_e32 v109, v109
	v_exp_f32_e32 v110, v110
	v_exp_f32_e32 v111, v111
	v_cvt_pk_bf16_f32 v162, v104, v105
	v_cvt_pk_bf16_f32 v163, v106, v107
	v_cvt_pk_bf16_f32 v164, v108, v109
	v_cvt_pk_bf16_f32 v165, v110, v111
	v_pk_add_f32 v[130:131], v[130:131], v[104:105]
	v_pk_add_f32 v[130:131], v[130:131], v[106:107]
	v_pk_add_f32 v[130:131], v[130:131], v[108:109]
	v_pk_add_f32 v[130:131], v[130:131], v[110:111]
	v_mfma_f32_32x32x16_bf16 v[80:95], v[162:165], v[176:179], v[80:95]
	v_exp_f32_e32 v112, v112
	v_exp_f32_e32 v113, v113
	v_exp_f32_e32 v114, v114
	v_exp_f32_e32 v115, v115
	v_mfma_f32_32x32x16_bf16 v[200:215], v[162:165], v[180:183], v[200:215]
	v_exp_f32_e32 v116, v116
	v_exp_f32_e32 v117, v117
	v_exp_f32_e32 v118, v118
	v_exp_f32_e32 v119, v119
	v_cvt_pk_bf16_f32 v162, v112, v113
	v_cvt_pk_bf16_f32 v163, v114, v115
	v_cvt_pk_bf16_f32 v164, v116, v117
	v_cvt_pk_bf16_f32 v165, v118, v119
	v_pk_add_f32 v[130:131], v[130:131], v[112:113]
	v_pk_add_f32 v[130:131], v[130:131], v[114:115]
	v_pk_add_f32 v[130:131], v[130:131], v[116:117]
	v_pk_add_f32 v[130:131], v[130:131], v[118:119]
	v_mfma_f32_32x32x16_bf16 v[80:95], v[162:165], v[184:187], v[80:95]
	v_exp_f32_e32 v120, v120
	v_exp_f32_e32 v121, v121
	v_exp_f32_e32 v122, v122
	v_exp_f32_e32 v123, v123
	v_mfma_f32_32x32x16_bf16 v[200:215], v[162:165], v[188:191], v[200:215]
	v_exp_f32_e32 v124, v124
	v_exp_f32_e32 v125, v125
	v_exp_f32_e32 v126, v126
	v_exp_f32_e32 v127, v127
	v_cvt_pk_bf16_f32 v162, v120, v121
	v_cvt_pk_bf16_f32 v163, v122, v123
	v_cvt_pk_bf16_f32 v164, v124, v125
	v_cvt_pk_bf16_f32 v165, v126, v127
	v_pk_add_f32 v[130:131], v[130:131], v[120:121]
	v_pk_add_f32 v[130:131], v[130:131], v[122:123]
	v_pk_add_f32 v[130:131], v[130:131], v[124:125]
	v_pk_add_f32 v[130:131], v[130:131], v[126:127]
	s_waitcnt vmcnt(4)
	s_waitcnt lgkmcnt(0)
	s_barrier
	s_cmp_eq_u32 s33, 21
	s_cbranch_scc1 .Lat_ndF1
	s_add_u32 m0, s51, 0x0
	s_nop 0
	global_load_lds_dwordx4 v158, s[36:37]
	s_add_u32 m0, s51, 0x2000
	s_nop 0
	global_load_lds_dwordx4 v159, s[36:37]
	s_add_u32 m0, s51, 0xc000
	s_nop 0
	global_load_lds_dwordx4 v160, s[48:49]
	s_add_u32 m0, s51, 0xe000
	s_nop 0
	global_load_lds_dwordx4 v161, s[48:49]
	s_add_u32 s36, s36, 0x4000
	s_addc_u32 s37, s37, 0
	s_add_u32 s48, s48, 0x4000
	s_addc_u32 s49, s49, 0
.Lat_ndF1:
	ds_read_b128 v[48:51], v144 offset:16384
	ds_read_b128 v[52:55], v145 offset:16384
	ds_read_b128 v[56:59], v144 offset:20480
	ds_read_b128 v[60:63], v145 offset:20480
	v_mfma_f32_32x32x16_bf16 v[80:95], v[162:165], v[192:195], v[80:95]
	v_mfma_f32_32x32x16_bf16 v[200:215], v[162:165], v[196:199], v[200:215]
	s_waitcnt lgkmcnt(0)
	v_mfma_f32_32x32x16_bf16 v[96:111], v[48:51], v[136:139], 0
	ds_read_b64_tr_b16 v[168:169], v146 offset:16384
	ds_read_b64_tr_b16 v[170:171], v146 offset:17408
	ds_read_b64_tr_b16 v[172:173], v146 offset:16896
	ds_read_b64_tr_b16 v[174:175], v146 offset:17920
	v_mfma_f32_32x32x16_bf16 v[96:111], v[52:55], v[140:143], v[96:111]
	ds_read_b64_tr_b16 v[176:177], v146 offset:18432
	ds_read_b64_tr_b16 v[178:179], v146 offset:19456
	ds_read_b64_tr_b16 v[180:181], v146 offset:18944
	ds_read_b64_tr_b16 v[182:183], v146 offset:19968
	v_mfma_f32_32x32x16_bf16 v[112:127], v[56:59], v[136:139], 0
	ds_read_b64_tr_b16 v[184:185], v146 offset:20480
	ds_read_b64_tr_b16 v[186:187], v146 offset:21504
	ds_read_b64_tr_b16 v[188:189], v146 offset:20992
	ds_read_b64_tr_b16 v[190:191], v146 offset:22016
	v_mfma_f32_32x32x16_bf16 v[112:127], v[60:63], v[140:143], v[112:127]
	ds_read_b64_tr_b16 v[192:193], v146 offset:22528
	ds_read_b64_tr_b16 v[194:195], v146 offset:23552
	ds_read_b64_tr_b16 v[196:197], v146 offset:23040
	ds_read_b64_tr_b16 v[198:199], v146 offset:24064
	v_exp_f32_e32 v96, v96
	v_exp_f32_e32 v97, v97
	v_exp_f32_e32 v98, v98
	v_exp_f32_e32 v99, v99
	v_exp_f32_e32 v100, v100
	v_exp_f32_e32 v101, v101
	v_exp_f32_e32 v102, v102
	v_exp_f32_e32 v103, v103
	v_cvt_pk_bf16_f32 v162, v96, v97
	v_cvt_pk_bf16_f32 v163, v98, v99
	v_cvt_pk_bf16_f32 v164, v100, v101
	v_cvt_pk_bf16_f32 v165, v102, v103
	v_pk_add_f32 v[128:129], v[128:129], v[96:97]
	v_pk_add_f32 v[128:129], v[128:129], v[98:99]
	v_pk_add_f32 v[128:129], v[128:129], v[100:101]
	v_pk_add_f32 v[128:129], v[128:129], v[102:103]
	s_waitcnt lgkmcnt(12)
	v_mfma_f32_32x32x16_bf16 v[0:15], v[162:165], v[168:171], v[0:15]
	v_exp_f32_e32 v104, v104
	v_exp_f32_e32 v105, v105
	v_exp_f32_e32 v106, v106
	v_exp_f32_e32 v107, v107
	v_mfma_f32_32x32x16_bf16 v[16:31], v[162:165], v[172:175], v[16:31]
	v_exp_f32_e32 v108, v108
	v_exp_f32_e32 v109, v109
	v_exp_f32_e32 v110, v110
	v_exp_f32_e32 v111, v111
	v_cvt_pk_bf16_f32 v162, v104, v105
	v_cvt_pk_bf16_f32 v163, v106, v107
	v_cvt_pk_bf16_f32 v164, v108, v109
	v_cvt_pk_bf16_f32 v165, v110, v111
	v_pk_add_f32 v[128:129], v[128:129], v[104:105]
	v_pk_add_f32 v[128:129], v[128:129], v[106:107]
	v_pk_add_f32 v[128:129], v[128:129], v[108:109]
	v_pk_add_f32 v[128:129], v[128:129], v[110:111]
	s_waitcnt lgkmcnt(8)
	v_mfma_f32_32x32x16_bf16 v[0:15], v[162:165], v[176:179], v[0:15]
	v_exp_f32_e32 v112, v112
	v_exp_f32_e32 v113, v113
	v_exp_f32_e32 v114, v114
	v_exp_f32_e32 v115, v115
	v_mfma_f32_32x32x16_bf16 v[16:31], v[162:165], v[180:183], v[16:31]
	v_mfma_f32_32x32x16_bf16 v[96:111], v[48:51], v[150:153], 0
	v_exp_f32_e32 v116, v116
	v_exp_f32_e32 v117, v117
	v_exp_f32_e32 v118, v118
	v_exp_f32_e32 v119, v119
	v_mfma_f32_32x32x16_bf16 v[96:111], v[52:55], v[154:157], v[96:111]
	v_cvt_pk_bf16_f32 v162, v112, v113
	v_cvt_pk_bf16_f32 v163, v114, v115
	v_cvt_pk_bf16_f32 v164, v116, v117
	v_cvt_pk_bf16_f32 v165, v118, v119
	v_pk_add_f32 v[128:129], v[128:129], v[112:113]
	v_pk_add_f32 v[128:129], v[128:129], v[114:115]
	v_pk_add_f32 v[128:129], v[128:129], v[116:117]
	v_pk_add_f32 v[128:129], v[128:129], v[118:119]
	s_waitcnt lgkmcnt(4)
	v_mfma_f32_32x32x16_bf16 v[0:15], v[162:165], v[184:187], v[0:15]
	v_exp_f32_e32 v120, v120
	v_exp_f32_e32 v121, v121
	v_exp_f32_e32 v122, v122
	v_exp_f32_e32 v123, v123
	v_mfma_f32_32x32x16_bf16 v[16:31], v[162:165], v[188:191], v[16:31]
	v_exp_f32_e32 v124, v124
	v_exp_f32_e32 v125, v125
	v_exp_f32_e32 v126, v126
	v_exp_f32_e32 v127, v127
	v_cvt_pk_bf16_f32 v162, v120, v121
	v_cvt_pk_bf16_f32 v163, v122, v123
	v_cvt_pk_bf16_f32 v164, v124, v125
	v_cvt_pk_bf16_f32 v165, v126, v127
	v_pk_add_f32 v[128:129], v[128:129], v[120:121]
	v_pk_add_f32 v[128:129], v[128:129], v[122:123]
	v_pk_add_f32 v[128:129], v[128:129], v[124:125]
	v_pk_add_f32 v[128:129], v[128:129], v[126:127]
	v_mfma_f32_32x32x16_bf16 v[112:127], v[56:59], v[150:153], 0
	v_mfma_f32_32x32x16_bf16 v[112:127], v[60:63], v[154:157], v[112:127]
	s_waitcnt lgkmcnt(0)
	v_mfma_f32_32x32x16_bf16 v[0:15], v[162:165], v[192:195], v[0:15]
	v_mfma_f32_32x32x16_bf16 v[16:31], v[162:165], v[196:199], v[16:31]
	ds_read_b128 v[48:51], v144 offset:24576
	ds_read_b128 v[52:55], v145 offset:24576
	ds_read_b128 v[56:59], v144 offset:28672
	ds_read_b128 v[60:63], v145 offset:28672
	v_exp_f32_e32 v96, v96
	v_exp_f32_e32 v97, v97
	v_exp_f32_e32 v98, v98
	v_exp_f32_e32 v99, v99
	v_exp_f32_e32 v100, v100
	v_exp_f32_e32 v101, v101
	v_exp_f32_e32 v102, v102
	v_exp_f32_e32 v103, v103
	v_cvt_pk_bf16_f32 v162, v96, v97
	v_cvt_pk_bf16_f32 v163, v98, v99
	v_cvt_pk_bf16_f32 v164, v100, v101
	v_cvt_pk_bf16_f32 v165, v102, v103
	v_pk_add_f32 v[130:131], v[130:131], v[96:97]
	v_pk_add_f32 v[130:131], v[130:131], v[98:99]
	v_pk_add_f32 v[130:131], v[130:131], v[100:101]
	v_pk_add_f32 v[130:131], v[130:131], v[102:103]
	v_mfma_f32_32x32x16_bf16 v[80:95], v[162:165], v[168:171], v[80:95]
	v_exp_f32_e32 v104, v104
	v_exp_f32_e32 v105, v105
	v_exp_f32_e32 v106, v106
	v_exp_f32_e32 v107, v107
	v_mfma_f32_32x32x16_bf16 v[200:215], v[162:165], v[172:175], v[200:215]
	v_exp_f32_e32 v108, v108
	v_exp_f32_e32 v109, v109
	v_exp_f32_e32 v110, v110
	v_exp_f32_e32 v111, v111
	v_cvt_pk_bf16_f32 v162, v104, v105
	v_cvt_pk_bf16_f32 v163, v106, v107
	v_cvt_pk_bf16_f32 v164, v108, v109
	v_cvt_pk_bf16_f32 v165, v110, v111
	v_pk_add_f32 v[130:131], v[130:131], v[104:105]
	v_pk_add_f32 v[130:131], v[130:131], v[106:107]
	v_pk_add_f32 v[130:131], v[130:131], v[108:109]
	v_pk_add_f32 v[130:131], v[130:131], v[110:111]
	v_mfma_f32_32x32x16_bf16 v[80:95], v[162:165], v[176:179], v[80:95]
	v_exp_f32_e32 v112, v112
	v_exp_f32_e32 v113, v113
	v_exp_f32_e32 v114, v114
	v_exp_f32_e32 v115, v115
	v_mfma_f32_32x32x16_bf16 v[200:215], v[162:165], v[180:183], v[200:215]
	v_exp_f32_e32 v116, v116
	v_exp_f32_e32 v117, v117
	v_exp_f32_e32 v118, v118
	v_exp_f32_e32 v119, v119
	v_cvt_pk_bf16_f32 v162, v112, v113
	v_cvt_pk_bf16_f32 v163, v114, v115
	v_cvt_pk_bf16_f32 v164, v116, v117
	v_cvt_pk_bf16_f32 v165, v118, v119
	v_pk_add_f32 v[130:131], v[130:131], v[112:113]
	v_pk_add_f32 v[130:131], v[130:131], v[114:115]
	v_pk_add_f32 v[130:131], v[130:131], v[116:117]
	v_pk_add_f32 v[130:131], v[130:131], v[118:119]
	v_mfma_f32_32x32x16_bf16 v[80:95], v[162:165], v[184:187], v[80:95]
	v_exp_f32_e32 v120, v120
	v_exp_f32_e32 v121, v121
	v_exp_f32_e32 v122, v122
	v_exp_f32_e32 v123, v123
	v_mfma_f32_32x32x16_bf16 v[200:215], v[162:165], v[188:191], v[200:215]
	v_exp_f32_e32 v124, v124
	v_exp_f32_e32 v125, v125
	v_exp_f32_e32 v126, v126
	v_exp_f32_e32 v127, v127
	v_cvt_pk_bf16_f32 v162, v120, v121
	v_cvt_pk_bf16_f32 v163, v122, v123
	v_cvt_pk_bf16_f32 v164, v124, v125
	v_cvt_pk_bf16_f32 v165, v126, v127
	v_pk_add_f32 v[130:131], v[130:131], v[120:121]
	v_pk_add_f32 v[130:131], v[130:131], v[122:123]
	v_pk_add_f32 v[130:131], v[130:131], v[124:125]
	v_pk_add_f32 v[130:131], v[130:131], v[126:127]
	v_mfma_f32_32x32x16_bf16 v[80:95], v[162:165], v[192:195], v[80:95]
	v_mfma_f32_32x32x16_bf16 v[200:215], v[162:165], v[196:199], v[200:215]
	s_waitcnt lgkmcnt(0)
	v_mfma_f32_32x32x16_bf16 v[96:111], v[48:51], v[136:139], 0
	ds_read_b64_tr_b16 v[168:169], v146 offset:24576
	ds_read_b64_tr_b16 v[170:171], v146 offset:25600
	ds_read_b64_tr_b16 v[172:173], v146 offset:25088
	ds_read_b64_tr_b16 v[174:175], v146 offset:26112
	v_mfma_f32_32x32x16_bf16 v[96:111], v[52:55], v[140:143], v[96:111]
	ds_read_b64_tr_b16 v[176:177], v146 offset:26624
	ds_read_b64_tr_b16 v[178:179], v146 offset:27648
	ds_read_b64_tr_b16 v[180:181], v146 offset:27136
	ds_read_b64_tr_b16 v[182:183], v146 offset:28160
	v_mfma_f32_32x32x16_bf16 v[112:127], v[56:59], v[136:139], 0
	ds_read_b64_tr_b16 v[184:185], v146 offset:28672
	ds_read_b64_tr_b16 v[186:187], v146 offset:29696
	ds_read_b64_tr_b16 v[188:189], v146 offset:29184
	ds_read_b64_tr_b16 v[190:191], v146 offset:30208
	v_mfma_f32_32x32x16_bf16 v[112:127], v[60:63], v[140:143], v[112:127]
	ds_read_b64_tr_b16 v[192:193], v146 offset:30720
	ds_read_b64_tr_b16 v[194:195], v146 offset:31744
	ds_read_b64_tr_b16 v[196:197], v146 offset:31232
	ds_read_b64_tr_b16 v[198:199], v146 offset:32256
	v_exp_f32_e32 v96, v96
	v_exp_f32_e32 v97, v97
	v_exp_f32_e32 v98, v98
	v_exp_f32_e32 v99, v99
	v_exp_f32_e32 v100, v100
	v_exp_f32_e32 v101, v101
	v_exp_f32_e32 v102, v102
	v_exp_f32_e32 v103, v103
	v_cvt_pk_bf16_f32 v162, v96, v97
	v_cvt_pk_bf16_f32 v163, v98, v99
	v_cvt_pk_bf16_f32 v164, v100, v101
	v_cvt_pk_bf16_f32 v165, v102, v103
	v_pk_add_f32 v[128:129], v[128:129], v[96:97]
	v_pk_add_f32 v[128:129], v[128:129], v[98:99]
	v_pk_add_f32 v[128:129], v[128:129], v[100:101]
	v_pk_add_f32 v[128:129], v[128:129], v[102:103]
	s_waitcnt lgkmcnt(12)
	v_mfma_f32_32x32x16_bf16 v[0:15], v[162:165], v[168:171], v[0:15]
	v_exp_f32_e32 v104, v104
	v_exp_f32_e32 v105, v105
	v_exp_f32_e32 v106, v106
	v_exp_f32_e32 v107, v107
	v_mfma_f32_32x32x16_bf16 v[16:31], v[162:165], v[172:175], v[16:31]
	v_exp_f32_e32 v108, v108
	v_exp_f32_e32 v109, v109
	v_exp_f32_e32 v110, v110
	v_exp_f32_e32 v111, v111
	v_cvt_pk_bf16_f32 v162, v104, v105
	v_cvt_pk_bf16_f32 v163, v106, v107
	v_cvt_pk_bf16_f32 v164, v108, v109
	v_cvt_pk_bf16_f32 v165, v110, v111
	v_pk_add_f32 v[128:129], v[128:129], v[104:105]
	v_pk_add_f32 v[128:129], v[128:129], v[106:107]
	v_pk_add_f32 v[128:129], v[128:129], v[108:109]
	v_pk_add_f32 v[128:129], v[128:129], v[110:111]
	s_waitcnt lgkmcnt(8)
	v_mfma_f32_32x32x16_bf16 v[0:15], v[162:165], v[176:179], v[0:15]
	v_exp_f32_e32 v112, v112
	v_exp_f32_e32 v113, v113
	v_exp_f32_e32 v114, v114
	v_exp_f32_e32 v115, v115
	v_mfma_f32_32x32x16_bf16 v[16:31], v[162:165], v[180:183], v[16:31]
	v_mfma_f32_32x32x16_bf16 v[96:111], v[48:51], v[150:153], 0
	v_exp_f32_e32 v116, v116
	v_exp_f32_e32 v117, v117
	v_exp_f32_e32 v118, v118
	v_exp_f32_e32 v119, v119
	v_mfma_f32_32x32x16_bf16 v[96:111], v[52:55], v[154:157], v[96:111]
	v_cvt_pk_bf16_f32 v162, v112, v113
	v_cvt_pk_bf16_f32 v163, v114, v115
	v_cvt_pk_bf16_f32 v164, v116, v117
	v_cvt_pk_bf16_f32 v165, v118, v119
	v_pk_add_f32 v[128:129], v[128:129], v[112:113]
	v_pk_add_f32 v[128:129], v[128:129], v[114:115]
	v_pk_add_f32 v[128:129], v[128:129], v[116:117]
	v_pk_add_f32 v[128:129], v[128:129], v[118:119]
	s_waitcnt lgkmcnt(4)
	v_mfma_f32_32x32x16_bf16 v[0:15], v[162:165], v[184:187], v[0:15]
	v_exp_f32_e32 v120, v120
	v_exp_f32_e32 v121, v121
	v_exp_f32_e32 v122, v122
	v_exp_f32_e32 v123, v123
	v_mfma_f32_32x32x16_bf16 v[16:31], v[162:165], v[188:191], v[16:31]
	v_exp_f32_e32 v124, v124
	v_exp_f32_e32 v125, v125
	v_exp_f32_e32 v126, v126
	v_exp_f32_e32 v127, v127
	v_cvt_pk_bf16_f32 v162, v120, v121
	v_cvt_pk_bf16_f32 v163, v122, v123
	v_cvt_pk_bf16_f32 v164, v124, v125
	v_cvt_pk_bf16_f32 v165, v126, v127
	v_pk_add_f32 v[128:129], v[128:129], v[120:121]
	v_pk_add_f32 v[128:129], v[128:129], v[122:123]
	v_pk_add_f32 v[128:129], v[128:129], v[124:125]
	v_pk_add_f32 v[128:129], v[128:129], v[126:127]
	v_mfma_f32_32x32x16_bf16 v[112:127], v[56:59], v[150:153], 0
	v_mfma_f32_32x32x16_bf16 v[112:127], v[60:63], v[154:157], v[112:127]
	s_waitcnt lgkmcnt(0)
	v_mfma_f32_32x32x16_bf16 v[0:15], v[162:165], v[192:195], v[0:15]
	v_mfma_f32_32x32x16_bf16 v[16:31], v[162:165], v[196:199], v[16:31]
	v_exp_f32_e32 v96, v96
	v_exp_f32_e32 v97, v97
	v_exp_f32_e32 v98, v98
	v_exp_f32_e32 v99, v99
	v_exp_f32_e32 v100, v100
	v_exp_f32_e32 v101, v101
	v_exp_f32_e32 v102, v102
	v_exp_f32_e32 v103, v103
	v_cvt_pk_bf16_f32 v162, v96, v97
	v_cvt_pk_bf16_f32 v163, v98, v99
	v_cvt_pk_bf16_f32 v164, v100, v101
	v_cvt_pk_bf16_f32 v165, v102, v103
	v_pk_add_f32 v[130:131], v[130:131], v[96:97]
	v_pk_add_f32 v[130:131], v[130:131], v[98:99]
	v_pk_add_f32 v[130:131], v[130:131], v[100:101]
	v_pk_add_f32 v[130:131], v[130:131], v[102:103]
	v_mfma_f32_32x32x16_bf16 v[80:95], v[162:165], v[168:171], v[80:95]
	v_exp_f32_e32 v104, v104
	v_exp_f32_e32 v105, v105
	v_exp_f32_e32 v106, v106
	v_exp_f32_e32 v107, v107
	v_mfma_f32_32x32x16_bf16 v[200:215], v[162:165], v[172:175], v[200:215]
	v_exp_f32_e32 v108, v108
	v_exp_f32_e32 v109, v109
	v_exp_f32_e32 v110, v110
	v_exp_f32_e32 v111, v111
	v_cvt_pk_bf16_f32 v162, v104, v105
	v_cvt_pk_bf16_f32 v163, v106, v107
	v_cvt_pk_bf16_f32 v164, v108, v109
	v_cvt_pk_bf16_f32 v165, v110, v111
	v_pk_add_f32 v[130:131], v[130:131], v[104:105]
	v_pk_add_f32 v[130:131], v[130:131], v[106:107]
	v_pk_add_f32 v[130:131], v[130:131], v[108:109]
	v_pk_add_f32 v[130:131], v[130:131], v[110:111]
	v_mfma_f32_32x32x16_bf16 v[80:95], v[162:165], v[176:179], v[80:95]
	v_exp_f32_e32 v112, v112
	v_exp_f32_e32 v113, v113
	v_exp_f32_e32 v114, v114
	v_exp_f32_e32 v115, v115
	v_mfma_f32_32x32x16_bf16 v[200:215], v[162:165], v[180:183], v[200:215]
	v_exp_f32_e32 v116, v116
	v_exp_f32_e32 v117, v117
	v_exp_f32_e32 v118, v118
	v_exp_f32_e32 v119, v119
	v_cvt_pk_bf16_f32 v162, v112, v113
	v_cvt_pk_bf16_f32 v163, v114, v115
	v_cvt_pk_bf16_f32 v164, v116, v117
	v_cvt_pk_bf16_f32 v165, v118, v119
	v_pk_add_f32 v[130:131], v[130:131], v[112:113]
	v_pk_add_f32 v[130:131], v[130:131], v[114:115]
	v_pk_add_f32 v[130:131], v[130:131], v[116:117]
	v_pk_add_f32 v[130:131], v[130:131], v[118:119]
	v_mfma_f32_32x32x16_bf16 v[80:95], v[162:165], v[184:187], v[80:95]
	v_exp_f32_e32 v120, v120
	v_exp_f32_e32 v121, v121
	v_exp_f32_e32 v122, v122
	v_exp_f32_e32 v123, v123
	v_mfma_f32_32x32x16_bf16 v[200:215], v[162:165], v[188:191], v[200:215]
	v_exp_f32_e32 v124, v124
	v_exp_f32_e32 v125, v125
	v_exp_f32_e32 v126, v126
	v_exp_f32_e32 v127, v127
	v_cvt_pk_bf16_f32 v162, v120, v121
	v_cvt_pk_bf16_f32 v163, v122, v123
	v_cvt_pk_bf16_f32 v164, v124, v125
	v_cvt_pk_bf16_f32 v165, v126, v127
	v_pk_add_f32 v[130:131], v[130:131], v[120:121]
	v_pk_add_f32 v[130:131], v[130:131], v[122:123]
	v_pk_add_f32 v[130:131], v[130:131], v[124:125]
	v_pk_add_f32 v[130:131], v[130:131], v[126:127]
	s_cmp_eq_u32 s33, 21
	s_cbranch_scc1 .Lat_w0F3
	s_waitcnt vmcnt(4)
	s_branch .Lat_wdF3

; #define AT_LOAD(K0, K1, V0, V1, T) do { const size_t e_ = (size_t)(128 * (T) + sr) * 64 + sc; \
;         K0 = *(const bf16x8*)(kcp + e_); V0 = *(const bf16x8*)(vcp + e_); K1 = *(const bf16x8*)(kcp + e_ + 64 * 64); V1 = *(const bf16x8*)(vcp + e_ + 64 * 64); } while (0)
; #define AT_STORE(K0, K1, V0, V1, BUF) do { *(LAS bf16x8*)(lds + AT_K + (BUF) * AT_KB + kst0) = K0; *(LAS bf16x8*)(lds + AT_K + (BUF) * AT_KB + kst1) = K1; \
;         *(LAS bf16x8*)(lds + AT_V + (BUF) * AT_VB + vst0) = V0; *(LAS bf16x8*)(lds + AT_V + (BUF) * AT_VB + vst1) = V1; } while (0)
; template <int VAR>
; __device__ __forceinline__ void attn_unit(const Args& a, int l, int b, int h, int qrow0  , bool ctxu, const bf16* Z, bf16* Y, LAS unsigned char* lds) {
;     ...
;     for (int t = 0; t < NT; t += 2) {
;         __syncthreads();
;         if (t + 2 < NT) AT_LOAD(ka0, ka1, va0, va1, t + 2);
;         attn_tile(Kb0, vb0, q0, q1, negm, m, o0, o1, lacc, t == 0, wsf, r32, hi);
;         AT_STORE(kb0, kb1, vb0_, vb1_, 1);
;         __syncthreads();
;         if (t + 3 < NT) AT_LOAD(kb0, kb1, vb0_, vb1_, t + 3);
;         attn_tile(Kb0 + AT_KB, vb0 + AT_VB, q0, q1, negm, m, o0, o1, lacc, false, wsf, r32, hi);
;         if (t + 2 < NT) AT_STORE(ka0, ka1, va0, va1, 0);
.Lat_ndF3:
	ds_read_b128 v[48:51], v144 offset:32768
	ds_read_b128 v[52:55], v145 offset:32768
	ds_read_b128 v[56:59], v144 offset:36864
	ds_read_b128 v[60:63], v145 offset:36864
	v_mfma_f32_32x32x16_bf16 v[80:95], v[162:165], v[192:195], v[80:95]
	v_mfma_f32_32x32x16_bf16 v[200:215], v[162:165], v[196:199], v[200:215]
	s_waitcnt lgkmcnt(0)
	v_mfma_f32_32x32x16_bf16 v[96:111], v[48:51], v[136:139], 0
	ds_read_b64_tr_b16 v[168:169], v146 offset:32768
	ds_read_b64_tr_b16 v[170:171], v146 offset:33792
	ds_read_b64_tr_b16 v[172:173], v146 offset:33280
	ds_read_b64_tr_b16 v[174:175], v146 offset:34304
	v_mfma_f32_32x32x16_bf16 v[96:111], v[52:55], v[140:143], v[96:111]
	ds_read_b64_tr_b16 v[176:177], v146 offset:34816
	ds_read_b64_tr_b16 v[178:179], v146 offset:35840
	ds_read_b64_tr_b16 v[180:181], v146 offset:35328
	ds_read_b64_tr_b16 v[182:183], v146 offset:36352
	v_mfma_f32_32x32x16_bf16 v[112:127], v[56:59], v[136:139], 0
	ds_read_b64_tr_b16 v[184:185], v146 offset:36864
	ds_read_b64_tr_b16 v[186:187], v146 offset:37888
	ds_read_b64_tr_b16 v[188:189], v146 offset:37376
	ds_read_b64_tr_b16 v[190:191], v146 offset:38400
	v_mfma_f32_32x32x16_bf16 v[112:127], v[60:63], v[140:143], v[112:127]
	ds_read_b64_tr_b16 v[192:193], v146 offset:38912
	ds_read_b64_tr_b16 v[194:195], v146 offset:39936
	ds_read_b64_tr_b16 v[196:197], v146 offset:39424
	ds_read_b64_tr_b16 v[198:199], v146 offset:40448
	v_exp_f32_e32 v96, v96
	v_exp_f32_e32 v97, v97
	v_exp_f32_e32 v98, v98
	v_exp_f32_e32 v99, v99
	v_exp_f32_e32 v100, v100
	v_exp_f32_e32 v101, v101
	v_exp_f32_e32 v102, v102
	v_exp_f32_e32 v103, v103
	v_cvt_pk_bf16_f32 v162, v96, v97
	v_cvt_pk_bf16_f32 v163, v98, v99
	v_cvt_pk_bf16_f32 v164, v100, v101
	v_cvt_pk_bf16_f32 v165, v102, v103
	v_pk_add_f32 v[128:129], v[128:129], v[96:97]
	v_pk_add_f32 v[128:129], v[128:129], v[98:99]
	v_pk_add_f32 v[128:129], v[128:129], v[100:101]
	v_pk_add_f32 v[128:129], v[128:129], v[102:103]
	s_waitcnt lgkmcnt(12)
	v_mfma_f32_32x32x16_bf16 v[0:15], v[162:165], v[168:171], v[0:15]
	v_exp_f32_e32 v104, v104
	v_exp_f32_e32 v105, v105
	v_exp_f32_e32 v106, v106
	v_exp_f32_e32 v107, v107
	v_mfma_f32_32x32x16_bf16 v[16:31], v[162:165], v[172:175], v[16:31]
	v_exp_f32_e32 v108, v108
	v_exp_f32_e32 v109, v109
	v_exp_f32_e32 v110, v110
	v_exp_f32_e32 v111, v111
	v_cvt_pk_bf16_f32 v162, v104, v105
	v_cvt_pk_bf16_f32 v163, v106, v107
	v_cvt_pk_bf16_f32 v164, v108, v109
	v_cvt_pk_bf16_f32 v165, v110, v111
	v_pk_add_f32 v[128:129], v[128:129], v[104:105]
	v_pk_add_f32 v[128:129], v[128:129], v[106:107]
	v_pk_add_f32 v[128:129], v[128:129], v[108:109]
	v_pk_add_f32 v[128:129], v[128:129], v[110:111]
	s_waitcnt lgkmcnt(8)
	v_mfma_f32_32x32x16_bf16 v[0:15], v[162:165], v[176:179], v[0:15]
	v_exp_f32_e32 v112, v112
	v_exp_f32_e32 v113, v113
	v_exp_f32_e32 v114, v114
	v_exp_f32_e32 v115, v115
	v_mfma_f32_32x32x16_bf16 v[16:31], v[162:165], v[180:183], v[16:31]
	v_mfma_f32_32x32x16_bf16 v[96:111], v[48:51], v[150:153], 0
	v_exp_f32_e32 v116, v116
	v_exp_f32_e32 v117, v117
	v_exp_f32_e32 v118, v118
	v_exp_f32_e32 v119, v119
	v_mfma_f32_32x32x16_bf16 v[96:111], v[52:55], v[154:157], v[96:111]
	v_cvt_pk_bf16_f32 v162, v112, v113
	v_cvt_pk_bf16_f32 v163, v114, v115
	v_cvt_pk_bf16_f32 v164, v116, v117
	v_cvt_pk_bf16_f32 v165, v118, v119
	v_pk_add_f32 v[128:129], v[128:129], v[112:113]
	v_pk_add_f32 v[128:129], v[128:129], v[114:115]
	v_pk_add_f32 v[128:129], v[128:129], v[116:117]
	v_pk_add_f32 v[128:129], v[128:129], v[118:119]
	s_waitcnt lgkmcnt(4)
	v_mfma_f32_32x32x16_bf16 v[0:15], v[162:165], v[184:187], v[0:15]
	v_exp_f32_e32 v120, v120
	v_exp_f32_e32 v121, v121
	v_exp_f32_e32 v122, v122
	v_exp_f32_e32 v123, v123
	v_mfma_f32_32x32x16_bf16 v[16:31], v[162:165], v[188:191], v[16:31]
	v_exp_f32_e32 v124, v124
	v_exp_f32_e32 v125, v125
	v_exp_f32_e32 v126, v126
	v_exp_f32_e32 v127, v127
	v_cvt_pk_bf16_f32 v162, v120, v121
	v_cvt_pk_bf16_f32 v163, v122, v123
	v_cvt_pk_bf16_f32 v164, v124, v125
	v_cvt_pk_bf16_f32 v165, v126, v127
	v_pk_add_f32 v[128:129], v[128:129], v[120:121]
	v_pk_add_f32 v[128:129], v[128:129], v[122:123]
	v_pk_add_f32 v[128:129], v[128:129], v[124:125]
	v_pk_add_f32 v[128:129], v[128:129], v[126:127]
	v_mfma_f32_32x32x16_bf16 v[112:127], v[56:59], v[150:153], 0
	v_mfma_f32_32x32x16_bf16 v[112:127], v[60:63], v[154:157], v[112:127]
	s_waitcnt lgkmcnt(0)
	v_mfma_f32_32x32x16_bf16 v[0:15], v[162:165], v[192:195], v[0:15]
	v_mfma_f32_32x32x16_bf16 v[16:31], v[162:165], v[196:199], v[16:31]
	ds_read_b128 v[48:51], v144 offset:40960
	ds_read_b128 v[52:55], v145 offset:40960
	ds_read_b128 v[56:59], v144 offset:45056
	ds_read_b128 v[60:63], v145 offset:45056
	v_exp_f32_e32 v96, v96
	v_exp_f32_e32 v97, v97
	v_exp_f32_e32 v98, v98
	v_exp_f32_e32 v99, v99
	v_exp_f32_e32 v100, v100
	v_exp_f32_e32 v101, v101
	v_exp_f32_e32 v102, v102
	v_exp_f32_e32 v103, v103
	v_cvt_pk_bf16_f32 v162, v96, v97
	v_cvt_pk_bf16_f32 v163, v98, v99
	v_cvt_pk_bf16_f32 v164, v100, v101
	v_cvt_pk_bf16_f32 v165, v102, v103
	v_pk_add_f32 v[130:131], v[130:131], v[96:97]
	v_pk_add_f32 v[130:131], v[130:131], v[98:99]
	v_pk_add_f32 v[130:131], v[130:131], v[100:101]
	v_pk_add_f32 v[130:131], v[130:131], v[102:103]
	v_mfma_f32_32x32x16_bf16 v[80:95], v[162:165], v[168:171], v[80:95]
	v_exp_f32_e32 v104, v104
	v_exp_f32_e32 v105, v105
	v_exp_f32_e32 v106, v106
	v_exp_f32_e32 v107, v107
	v_mfma_f32_32x32x16_bf16 v[200:215], v[162:165], v[172:175], v[200:215]
	v_exp_f32_e32 v108, v108
	v_exp_f32_e32 v109, v109
	v_exp_f32_e32 v110, v110
	v_exp_f32_e32 v111, v111
	v_cvt_pk_bf16_f32 v162, v104, v105
	v_cvt_pk_bf16_f32 v163, v106, v107
	v_cvt_pk_bf16_f32 v164, v108, v109
	v_cvt_pk_bf16_f32 v165, v110, v111
	v_pk_add_f32 v[130:131], v[130:131], v[104:105]
	v_pk_add_f32 v[130:131], v[130:131], v[106:107]
	v_pk_add_f32 v[130:131], v[130:131], v[108:109]
	v_pk_add_f32 v[130:131], v[130:131], v[110:111]
	v_mfma_f32_32x32x16_bf16 v[80:95], v[162:165], v[176:179], v[80:95]
	v_exp_f32_e32 v112, v112
	v_exp_f32_e32 v113, v113
	v_exp_f32_e32 v114, v114
	v_exp_f32_e32 v115, v115
	v_mfma_f32_32x32x16_bf16 v[200:215], v[162:165], v[180:183], v[200:215]
	v_exp_f32_e32 v116, v116
	v_exp_f32_e32 v117, v117
	v_exp_f32_e32 v118, v118
	v_exp_f32_e32 v119, v119
	v_cvt_pk_bf16_f32 v162, v112, v113
	v_cvt_pk_bf16_f32 v163, v114, v115
	v_cvt_pk_bf16_f32 v164, v116, v117
	v_cvt_pk_bf16_f32 v165, v118, v119
	v_pk_add_f32 v[130:131], v[130:131], v[112:113]
	v_pk_add_f32 v[130:131], v[130:131], v[114:115]
	v_pk_add_f32 v[130:131], v[130:131], v[116:117]
	v_pk_add_f32 v[130:131], v[130:131], v[118:119]
	v_mfma_f32_32x32x16_bf16 v[80:95], v[162:165], v[184:187], v[80:95]
	v_exp_f32_e32 v120, v120
	v_exp_f32_e32 v121, v121
	v_exp_f32_e32 v122, v122
	v_exp_f32_e32 v123, v123
	v_mfma_f32_32x32x16_bf16 v[200:215], v[162:165], v[188:191], v[200:215]
	v_exp_f32_e32 v124, v124
	v_exp_f32_e32 v125, v125
	v_exp_f32_e32 v126, v126
	v_exp_f32_e32 v127, v127
	v_cvt_pk_bf16_f32 v162, v120, v121
	v_cvt_pk_bf16_f32 v163, v122, v123
	v_cvt_pk_bf16_f32 v164, v124, v125
	v_cvt_pk_bf16_f32 v165, v126, v127
	v_pk_add_f32 v[130:131], v[130:131], v[120:121]
	v_pk_add_f32 v[130:131], v[130:131], v[122:123]
	v_pk_add_f32 v[130:131], v[130:131], v[124:125]
	v_pk_add_f32 v[130:131], v[130:131], v[126:127]
	v_mfma_f32_32x32x16_bf16 v[80:95], v[162:165], v[192:195], v[80:95]
	v_mfma_f32_32x32x16_bf16 v[200:215], v[162:165], v[196:199], v[200:215]
	s_waitcnt lgkmcnt(0)
	v_mfma_f32_32x32x16_bf16 v[96:111], v[48:51], v[136:139], 0
	ds_read_b64_tr_b16 v[168:169], v146 offset:40960
	ds_read_b64_tr_b16 v[170:171], v146 offset:41984
	ds_read_b64_tr_b16 v[172:173], v146 offset:41472
	ds_read_b64_tr_b16 v[174:175], v146 offset:42496
	v_mfma_f32_32x32x16_bf16 v[96:111], v[52:55], v[140:143], v[96:111]
	ds_read_b64_tr_b16 v[176:177], v146 offset:43008
	ds_read_b64_tr_b16 v[178:179], v146 offset:44032
	ds_read_b64_tr_b16 v[180:181], v146 offset:43520
	ds_read_b64_tr_b16 v[182:183], v146 offset:44544
	v_mfma_f32_32x32x16_bf16 v[112:127], v[56:59], v[136:139], 0
	ds_read_b64_tr_b16 v[184:185], v146 offset:45056
	ds_read_b64_tr_b16 v[186:187], v146 offset:46080
	ds_read_b64_tr_b16 v[188:189], v146 offset:45568
	ds_read_b64_tr_b16 v[190:191], v146 offset:46592
	v_mfma_f32_32x32x16_bf16 v[112:127], v[60:63], v[140:143], v[112:127]
	ds_read_b64_tr_b16 v[192:193], v146 offset:47104
	ds_read_b64_tr_b16 v[194:195], v146 offset:48128
	ds_read_b64_tr_b16 v[196:197], v146 offset:47616
	ds_read_b64_tr_b16 v[198:199], v146 offset:48640
	v_exp_f32_e32 v96, v96
	v_exp_f32_e32 v97, v97
	v_exp_f32_e32 v98, v98
	v_exp_f32_e32 v99, v99
	v_exp_f32_e32 v100, v100
	v_exp_f32_e32 v101, v101
	v_exp_f32_e32 v102, v102
	v_exp_f32_e32 v103, v103
	v_cvt_pk_bf16_f32 v162, v96, v97
	v_cvt_pk_bf16_f32 v163, v98, v99
	v_cvt_pk_bf16_f32 v164, v100, v101
	v_cvt_pk_bf16_f32 v165, v102, v103
	v_pk_add_f32 v[128:129], v[128:129], v[96:97]
	v_pk_add_f32 v[128:129], v[128:129], v[98:99]
	v_pk_add_f32 v[128:129], v[128:129], v[100:101]
	v_pk_add_f32 v[128:129], v[128:129], v[102:103]
	s_waitcnt lgkmcnt(12)
	v_mfma_f32_32x32x16_bf16 v[0:15], v[162:165], v[168:171], v[0:15]
	v_exp_f32_e32 v104, v104
	v_exp_f32_e32 v105, v105
	v_exp_f32_e32 v106, v106
	v_exp_f32_e32 v107, v107
	v_mfma_f32_32x32x16_bf16 v[16:31], v[162:165], v[172:175], v[16:31]
	v_exp_f32_e32 v108, v108
	v_exp_f32_e32 v109, v109
	v_exp_f32_e32 v110, v110
	v_exp_f32_e32 v111, v111
	v_cvt_pk_bf16_f32 v162, v104, v105
	v_cvt_pk_bf16_f32 v163, v106, v107
	v_cvt_pk_bf16_f32 v164, v108, v109
	v_cvt_pk_bf16_f32 v165, v110, v111
	v_pk_add_f32 v[128:129], v[128:129], v[104:105]
	v_pk_add_f32 v[128:129], v[128:129], v[106:107]
	v_pk_add_f32 v[128:129], v[128:129], v[108:109]
	v_pk_add_f32 v[128:129], v[128:129], v[110:111]
	s_waitcnt lgkmcnt(8)
	v_mfma_f32_32x32x16_bf16 v[0:15], v[162:165], v[176:179], v[0:15]
	v_exp_f32_e32 v112, v112
	v_exp_f32_e32 v113, v113
	v_exp_f32_e32 v114, v114
	v_exp_f32_e32 v115, v115
	v_mfma_f32_32x32x16_bf16 v[16:31], v[162:165], v[180:183], v[16:31]
	v_mfma_f32_32x32x16_bf16 v[96:111], v[48:51], v[150:153], 0
	v_exp_f32_e32 v116, v116
	v_exp_f32_e32 v117, v117
	v_exp_f32_e32 v118, v118
	v_exp_f32_e32 v119, v119
	v_mfma_f32_32x32x16_bf16 v[96:111], v[52:55], v[154:157], v[96:111]
	v_cvt_pk_bf16_f32 v162, v112, v113
	v_cvt_pk_bf16_f32 v163, v114, v115
	v_cvt_pk_bf16_f32 v164, v116, v117
	v_cvt_pk_bf16_f32 v165, v118, v119
	v_pk_add_f32 v[128:129], v[128:129], v[112:113]
	v_pk_add_f32 v[128:129], v[128:129], v[114:115]
	v_pk_add_f32 v[128:129], v[128:129], v[116:117]
	v_pk_add_f32 v[128:129], v[128:129], v[118:119]
	s_waitcnt lgkmcnt(4)
	v_mfma_f32_32x32x16_bf16 v[0:15], v[162:165], v[184:187], v[0:15]
	v_exp_f32_e32 v120, v120
	v_exp_f32_e32 v121, v121
	v_exp_f32_e32 v122, v122
	v_exp_f32_e32 v123, v123
	v_mfma_f32_32x32x16_bf16 v[16:31], v[162:165], v[188:191], v[16:31]
	v_exp_f32_e32 v124, v124
	v_exp_f32_e32 v125, v125
	v_exp_f32_e32 v126, v126
	v_exp_f32_e32 v127, v127
	v_cvt_pk_bf16_f32 v162, v120, v121
	v_cvt_pk_bf16_f32 v163, v122, v123
	v_cvt_pk_bf16_f32 v164, v124, v125
	v_cvt_pk_bf16_f32 v165, v126, v127
	v_pk_add_f32 v[128:129], v[128:129], v[120:121]
	v_pk_add_f32 v[128:129], v[128:129], v[122:123]
	v_pk_add_f32 v[128:129], v[128:129], v[124:125]
	v_pk_add_f32 v[128:129], v[128:129], v[126:127]
	v_mfma_f32_32x32x16_bf16 v[112:127], v[56:59], v[150:153], 0
	v_mfma_f32_32x32x16_bf16 v[112:127], v[60:63], v[154:157], v[112:127]
	s_waitcnt lgkmcnt(0)
	v_mfma_f32_32x32x16_bf16 v[0:15], v[162:165], v[192:195], v[0:15]
	v_mfma_f32_32x32x16_bf16 v[16:31], v[162:165], v[196:199], v[16:31]
	v_exp_f32_e32 v96, v96
	v_exp_f32_e32 v97, v97
	v_exp_f32_e32 v98, v98
	v_exp_f32_e32 v99, v99
	v_exp_f32_e32 v100, v100
	v_exp_f32_e32 v101, v101
	v_exp_f32_e32 v102, v102
	v_exp_f32_e32 v103, v103
	v_cvt_pk_bf16_f32 v162, v96, v97
	v_cvt_pk_bf16_f32 v163, v98, v99
	v_cvt_pk_bf16_f32 v164, v100, v101
	v_cvt_pk_bf16_f32 v165, v102, v103
	v_pk_add_f32 v[130:131], v[130:131], v[96:97]
	v_pk_add_f32 v[130:131], v[130:131], v[98:99]
	v_pk_add_f32 v[130:131], v[130:131], v[100:101]
	v_pk_add_f32 v[130:131], v[130:131], v[102:103]
	v_mfma_f32_32x32x16_bf16 v[80:95], v[162:165], v[168:171], v[80:95]
	v_exp_f32_e32 v104, v104
	v_exp_f32_e32 v105, v105
	v_exp_f32_e32 v106, v106
	v_exp_f32_e32 v107, v107
	v_mfma_f32_32x32x16_bf16 v[200:215], v[162:165], v[172:175], v[200:215]
	v_exp_f32_e32 v108, v108
	v_exp_f32_e32 v109, v109
	v_exp_f32_e32 v110, v110
	v_exp_f32_e32 v111, v111
	v_cvt_pk_bf16_f32 v162, v104, v105
	v_cvt_pk_bf16_f32 v163, v106, v107
	v_cvt_pk_bf16_f32 v164, v108, v109
	v_cvt_pk_bf16_f32 v165, v110, v111
	v_pk_add_f32 v[130:131], v[130:131], v[104:105]
	v_pk_add_f32 v[130:131], v[130:131], v[106:107]
	v_pk_add_f32 v[130:131], v[130:131], v[108:109]
	v_pk_add_f32 v[130:131], v[130:131], v[110:111]
	v_mfma_f32_32x32x16_bf16 v[80:95], v[162:165], v[176:179], v[80:95]
	v_exp_f32_e32 v112, v112
	v_exp_f32_e32 v113, v113
	v_exp_f32_e32 v114, v114
	v_exp_f32_e32 v115, v115
	v_mfma_f32_32x32x16_bf16 v[200:215], v[162:165], v[180:183], v[200:215]
	v_exp_f32_e32 v116, v116
	v_exp_f32_e32 v117, v117
	v_exp_f32_e32 v118, v118
	v_exp_f32_e32 v119, v119
	v_cvt_pk_bf16_f32 v162, v112, v113
	v_cvt_pk_bf16_f32 v163, v114, v115
	v_cvt_pk_bf16_f32 v164, v116, v117
	v_cvt_pk_bf16_f32 v165, v118, v119
	v_pk_add_f32 v[130:131], v[130:131], v[112:113]
	v_pk_add_f32 v[130:131], v[130:131], v[114:115]
	v_pk_add_f32 v[130:131], v[130:131], v[116:117]
	v_pk_add_f32 v[130:131], v[130:131], v[118:119]
	v_mfma_f32_32x32x16_bf16 v[80:95], v[162:165], v[184:187], v[80:95]
	v_exp_f32_e32 v120, v120
	v_exp_f32_e32 v121, v121
	v_exp_f32_e32 v122, v122
	v_exp_f32_e32 v123, v123
	v_mfma_f32_32x32x16_bf16 v[200:215], v[162:165], v[188:191], v[200:215]
	v_exp_f32_e32 v124, v124
	v_exp_f32_e32 v125, v125
	v_exp_f32_e32 v126, v126
	v_exp_f32_e32 v127, v127
	v_cvt_pk_bf16_f32 v162, v120, v121
	v_cvt_pk_bf16_f32 v163, v122, v123
	v_cvt_pk_bf16_f32 v164, v124, v125
	v_cvt_pk_bf16_f32 v165, v126, v127
	v_pk_add_f32 v[130:131], v[130:131], v[120:121]
	v_pk_add_f32 v[130:131], v[130:131], v[122:123]
	v_pk_add_f32 v[130:131], v[130:131], v[124:125]
	v_pk_add_f32 v[130:131], v[130:131], v[126:127]
	s_cmp_eq_u32 s33, 21
	s_cbranch_scc1 .Lat_w0F5
	s_waitcnt vmcnt(4)
	s_branch .Lat_wdF5

; #define LAS __attribute__((address_space(3)))
; __device__ __forceinline__ int crow(int r, int hi) { return (r & 3) + 8 * (r >> 2) + 4 * hi; }
; #define AT_LOAD(K0, K1, V0, V1, T) do { const size_t e_ = (size_t)(128 * (T) + sr) * 64 + sc; \
;         K0 = *(const bf16x8*)(kcp + e_); V0 = *(const bf16x8*)(vcp + e_); K1 = *(const bf16x8*)(kcp + e_ + 64 * 64); V1 = *(const bf16x8*)(vcp + e_ + 64 * 64); } while (0)
; #define AT_STORE(K0, K1, V0, V1, BUF) do { *(LAS bf16x8*)(lds + AT_K + (BUF) * AT_KB + kst0) = K0; *(LAS bf16x8*)(lds + AT_K + (BUF) * AT_KB + kst1) = K1; \
;         *(LAS bf16x8*)(lds + AT_V + (BUF) * AT_VB + vst0) = V0; *(LAS bf16x8*)(lds + AT_V + (BUF) * AT_VB + vst1) = V1; } while (0)
; template <int VAR>
; __device__ __forceinline__ void attn_unit(const Args& a, int l, int b, int h, int qrow0  , bool ctxu, const bf16* Z, bf16* Y, LAS unsigned char* lds) {
;     ...
;     for (int t = 0; t < NT; t += 2) {
;         __syncthreads();
;         if (t + 2 < NT) AT_LOAD(ka0, ka1, va0, va1, t + 2);
;         attn_tile(Kb0, vb0, q0, q1, negm, m, o0, o1, lacc, t == 0, wsf, r32, hi);
;         AT_STORE(kb0, kb1, vb0_, vb1_, 1);
;         __syncthreads();
;         if (t + 3 < NT) AT_LOAD(kb0, kb1, vb0_, vb1_, t + 3);
;         attn_tile(Kb0 + AT_KB, vb0 + AT_VB, q0, q1, negm, m, o0, o1, lacc, false, wsf, r32, hi);
;         if (t + 2 < NT) AT_STORE(ka0, ka1, va0, va1, 0);
;     }
;     ...
;     float lam, omli;
;     { float s1 = 0.f, s2 = 0.f;
;       for (int i = 0; i < 32; ++i) { s1 += a.lam_q1[l * 32 + i] * a.lam_k1[l * 32 + i]; s2 += a.lam_q2[l * 32 + i] * a.lam_k2[l * 32 + i]; }
;       const float li = 0.8f - 0.6f * expf(-0.3f * (float)l); lam = expf(s1) - expf(s2) + li; omli = 1.f - li; }
;     LAS float* stg = (LAS float*)(lds + AT_ST) + wq * 2048;
;     if (comp == 1) {
; #pragma unroll
;         for (int r = 0; r < 16; ++r) { const int qr = crow(r, hi); const float il = lam * __builtin_amdgcn_rcpf(lacc[r]); stg[qr * 64 + r32] = o0[r] * il; stg[qr * 64 + 32 + r32] = o1[r] * il; }
;     }
;     __syncthreads();
;     if (comp == 0) {
; #pragma unroll
;         for (int r = 0; r < 16; ++r) { const int qr = crow(r, hi); const float il = __builtin_amdgcn_rcpf(lacc[r]); o0[r] = o0[r] * il - stg[qr * 64 + r32]; o1[r] = o1[r] * il - stg[qr * 64 + 32 + r32]; }
.Lat_ndF5:
	ds_read_b128 v[48:51], v144 offset:0
	ds_read_b128 v[52:55], v145 offset:0
	ds_read_b128 v[56:59], v144 offset:4096
	ds_read_b128 v[60:63], v145 offset:4096
	v_mfma_f32_32x32x16_bf16 v[80:95], v[162:165], v[192:195], v[80:95]
	v_mfma_f32_32x32x16_bf16 v[200:215], v[162:165], v[196:199], v[200:215]
	s_add_u32 s33, s33, 1
	s_cmp_lt_u32 s33, 22
	s_cbranch_scc1 .Lat_floop
	v_add_f32_e32 v132, v128, v129
	v_mov_b32_e32 v133, v132
	s_nop 1
	v_permlane32_swap_b32_e32 v132, v133
	v_add_f32_e32 v135, v132, v133
	v_add_f32_e32 v132, v130, v131
	v_mov_b32_e32 v133, v132
	s_nop 1
	v_permlane32_swap_b32_e32 v132, v133
	v_add_f32_e32 v130, v132, v133
	s_nop 7
	s_nop 7
	v_add_f32_e32 v132, v135, v130
	v_mov_b32_e32 v133, 0
	v_add_f32_e64 v132, v132, |v0|
	v_add_f32_e64 v133, v133, |v1|
	v_add_f32_e64 v132, v132, |v2|
	v_add_f32_e64 v133, v133, |v3|
	v_add_f32_e64 v132, v132, |v4|
	v_add_f32_e64 v133, v133, |v5|
	v_add_f32_e64 v132, v132, |v6|
	v_add_f32_e64 v133, v133, |v7|
	v_add_f32_e64 v132, v132, |v8|
	v_add_f32_e64 v133, v133, |v9|
	v_add_f32_e64 v132, v132, |v10|
	v_add_f32_e64 v133, v133, |v11|
	v_add_f32_e64 v132, v132, |v12|
	v_add_f32_e64 v133, v133, |v13|
	v_add_f32_e64 v132, v132, |v14|
	v_add_f32_e64 v133, v133, |v15|
	v_add_f32_e64 v132, v132, |v16|
	v_add_f32_e64 v133, v133, |v17|
	v_add_f32_e64 v132, v132, |v18|
	v_add_f32_e64 v133, v133, |v19|
	v_add_f32_e64 v132, v132, |v20|
	v_add_f32_e64 v133, v133, |v21|
	v_add_f32_e64 v132, v132, |v22|
	v_add_f32_e64 v133, v133, |v23|
	v_add_f32_e64 v132, v132, |v24|
	v_add_f32_e64 v133, v133, |v25|
	v_add_f32_e64 v132, v132, |v26|
	v_add_f32_e64 v133, v133, |v27|
	v_add_f32_e64 v132, v132, |v28|
	v_add_f32_e64 v133, v133, |v29|
	v_add_f32_e64 v132, v132, |v30|
	v_add_f32_e64 v133, v133, |v31|
	v_add_f32_e64 v132, v132, |v80|
	v_add_f32_e64 v133, v133, |v81|
	v_add_f32_e64 v132, v132, |v82|
	v_add_f32_e64 v133, v133, |v83|
	v_add_f32_e64 v132, v132, |v84|
	v_add_f32_e64 v133, v133, |v85|
	v_add_f32_e64 v132, v132, |v86|
	v_add_f32_e64 v133, v133, |v87|
	v_add_f32_e64 v132, v132, |v88|
	v_add_f32_e64 v133, v133, |v89|
	v_add_f32_e64 v132, v132, |v90|
	v_add_f32_e64 v133, v133, |v91|
	v_add_f32_e64 v132, v132, |v92|
	v_add_f32_e64 v133, v133, |v93|
	v_add_f32_e64 v132, v132, |v94|
	v_add_f32_e64 v133, v133, |v95|
	v_add_f32_e64 v132, v132, |v200|
	v_add_f32_e64 v133, v133, |v201|
	v_add_f32_e64 v132, v132, |v202|
	v_add_f32_e64 v133, v133, |v203|
	v_add_f32_e64 v132, v132, |v204|
	v_add_f32_e64 v133, v133, |v205|
	v_add_f32_e64 v132, v132, |v206|
	v_add_f32_e64 v133, v133, |v207|
	v_add_f32_e64 v132, v132, |v208|
	v_add_f32_e64 v133, v133, |v209|
	v_add_f32_e64 v132, v132, |v210|
	v_add_f32_e64 v133, v133, |v211|
	v_add_f32_e64 v132, v132, |v212|
	v_add_f32_e64 v133, v133, |v213|
	v_add_f32_e64 v132, v132, |v214|
	v_add_f32_e64 v133, v133, |v215|
	v_add_f32_e32 v132, v132, v133
	v_mov_b32_e32 v133, 0x76800000
	v_cmp_nlt_f32_e32 vcc, v132, v133
	v_min_f32_e32 v132, v135, v130
	v_mov_b32_e32 v133, 0x0d800000
	s_mov_b64 s[94:95], vcc
	v_cmp_nge_f32_e32 vcc, v132, v133
	s_or_b64 vcc, vcc, s[94:95]
	s_cmp_lg_u64 vcc, 0
	s_cselect_b32 s50, 1, 0
	v_mov_b32_e32 v134, 0x19880
	v_mov_b32_e32 v133, s50
	ds_or_b32 v134, v133
	s_waitcnt lgkmcnt(0)
	s_barrier
	ds_read_b32 v133, v134
	s_waitcnt lgkmcnt(0)
	v_readfirstlane_b32 s50, v133
	s_cmp_lg_u32 s50, 0
	s_cbranch_scc1 .Lat_safe_entry
	s_nop 7
	s_waitcnt lgkmcnt(0)
	ds_write_b32 v148, v135
	s_waitcnt lgkmcnt(0)
	ds_read_b128 v[32:35], v147 offset:0
	ds_read_b128 v[36:39], v147 offset:32
	ds_read_b128 v[40:43], v147 offset:64
	ds_read_b128 v[44:47], v147 offset:96
	s_waitcnt lgkmcnt(0)
	s_mov_b32 s93, 0
	s_waitcnt vmcnt(0)
	v_or_b32_e32 v132, s58, v228
	v_mov_b32_e32 v133, 0
	v_lshl_add_u64 v[132:133], v[132:133], 2, s[78:79]
	global_load_dwordx4 v[100:103], v[132:133], off offset:16
	global_load_dwordx4 v[96:99], v[132:133], off
	s_setprio 0
	s_branch .LBB0_459

; #define LAS __attribute__((address_space(3)))
; __device__ __forceinline__ int v_st_nat(int k, int c) { return ((k >> 3) * 2 + (c >> 5)) * 512 + ((k & 7) * 32 + (c & 31)) * 2; }
; __device__ __forceinline__ int v_rd_base(int lane) { return ((lane & 3) << 3) | (((lane >> 2) & 3) << 6) | (((lane >> 4) & 1) << 5) | (((lane >> 5) & 1) << 8); }
; #define AT_LOAD(K0, K1, V0, V1, T) do { const size_t e_ = (size_t)(128 * (T) + sr) * 64 + sc; \
;         K0 = *(const bf16x8*)(kcp + e_); V0 = *(const bf16x8*)(vcp + e_); K1 = *(const bf16x8*)(kcp + e_ + 64 * 64); V1 = *(const bf16x8*)(vcp + e_ + 64 * 64); } while (0)
; #define AT_STORE(K0, K1, V0, V1, BUF) do { *(LAS bf16x8*)(lds + AT_K + (BUF) * AT_KB + kst0) = K0; *(LAS bf16x8*)(lds + AT_K + (BUF) * AT_KB + kst1) = K1; \
;         *(LAS bf16x8*)(lds + AT_V + (BUF) * AT_VB + vst0) = V0; *(LAS bf16x8*)(lds + AT_V + (BUF) * AT_VB + vst1) = V1; } while (0)
; template <int VAR>
; __device__ __forceinline__ void attn_unit(const Args& a, int l, int b, int h, int qrow0  , bool ctxu, const bf16* Z, bf16* Y, LAS unsigned char* lds) {
;     ...
;     const int sr = tid >> 3, sc = (tid & 7) * 8;
;     const int kst0 = sr * 144 + sc * 2, kst1 = kst0 + 64 * 144, vst0 = v_st_nat(sr, sc), vst1 = v_st_nat(sr + 64, sc);
;     const int vb0 = (int)(unsigned)(uintptr_t)(lds + AT_V) + v_rd_base(lane);
;     LAS float* wsf = (LAS float*)(lds + AT_WS) + wave * 64;
;     f32x16 negm = f32x16{}, o0 = f32x16{}, o1 = f32x16{}, lacc = f32x16{};
;     float m = 0.f;
;     bf16x8 ka0, ka1, va0, va1, kb0, kb1, vb0_, vb1_;
;     ...
;     AT_LOAD(ka0, ka1, va0, va1, 0); AT_LOAD(kb0, kb1, vb0_, vb1_, 1); AT_STORE(ka0, ka1, va0, va1, 0);
;     const LAS unsigned char* Kb0 = lds + AT_K + comp * 64;
;     for (int t = 0; t < NT; t += 2) {
;         __syncthreads();
;         if (t + 2 < NT) AT_LOAD(ka0, ka1, va0, va1, t + 2);
.Lat_passB:
	s_mov_b32 s93, 1
	s_barrier
	v_mov_b32_e32 v0, v80
	v_mov_b32_e32 v16, v200
	v_mov_b32_e32 v1, v81
	v_mov_b32_e32 v17, v201
	v_mov_b32_e32 v2, v82
	v_mov_b32_e32 v18, v202
	v_mov_b32_e32 v3, v83
	v_mov_b32_e32 v19, v203
	v_mov_b32_e32 v4, v84
	v_mov_b32_e32 v20, v204
	v_mov_b32_e32 v5, v85
	v_mov_b32_e32 v21, v205
	v_mov_b32_e32 v6, v86
	v_mov_b32_e32 v22, v206
	v_mov_b32_e32 v7, v87
	v_mov_b32_e32 v23, v207
	v_mov_b32_e32 v8, v88
	v_mov_b32_e32 v24, v208
	v_mov_b32_e32 v9, v89
	v_mov_b32_e32 v25, v209
	v_mov_b32_e32 v10, v90
	v_mov_b32_e32 v26, v210
	v_mov_b32_e32 v11, v91
	v_mov_b32_e32 v27, v211
	v_mov_b32_e32 v12, v92
	v_mov_b32_e32 v28, v212
	v_mov_b32_e32 v13, v93
	v_mov_b32_e32 v29, v213
	v_mov_b32_e32 v14, v94
	v_mov_b32_e32 v30, v214
	v_mov_b32_e32 v15, v95
	v_mov_b32_e32 v31, v215
	s_waitcnt lgkmcnt(0)
	ds_write_b32 v148, v130
	s_waitcnt lgkmcnt(0)
	ds_read_b128 v[32:35], v147 offset:0
	ds_read_b128 v[36:39], v147 offset:32
	ds_read_b128 v[40:43], v147 offset:64
	ds_read_b128 v[44:47], v147 offset:96
	s_waitcnt lgkmcnt(0)
	v_mbcnt_lo_u32_b32 v227, -1, 0
	v_mbcnt_hi_u32_b32 v227, -1, v227
	s_or_b32 s60, s60, 0x1000
	s_bfe_u32 s9, s29, 0x20006
	s_ashr_i32 s8, s29, 8
	s_branch .LBB0_459
.Lat_safe_entry:
	s_barrier
	v_mov_b32_e32 v0, 0
	v_mov_b32_e32 v1, 0
	v_mov_b32_e32 v2, 0
	v_mov_b32_e32 v3, 0
	v_mov_b32_e32 v4, 0
	v_mov_b32_e32 v5, 0
	v_mov_b32_e32 v6, 0
	v_mov_b32_e32 v7, 0
	v_mov_b32_e32 v8, 0
	v_mov_b32_e32 v9, 0
	v_mov_b32_e32 v10, 0
	v_mov_b32_e32 v11, 0
	v_mov_b32_e32 v12, 0
	v_mov_b32_e32 v13, 0
	v_mov_b32_e32 v14, 0
	v_mov_b32_e32 v15, 0
	v_mov_b32_e32 v16, 0
	v_mov_b32_e32 v17, 0
	v_mov_b32_e32 v18, 0
	v_mov_b32_e32 v19, 0
	v_mov_b32_e32 v20, 0
	v_mov_b32_e32 v21, 0
	v_mov_b32_e32 v22, 0
	v_mov_b32_e32 v23, 0
	v_mov_b32_e32 v24, 0
	v_mov_b32_e32 v25, 0
	v_mov_b32_e32 v26, 0
	v_mov_b32_e32 v27, 0
	v_mov_b32_e32 v28, 0
	v_mov_b32_e32 v29, 0
	v_mov_b32_e32 v30, 0
	v_mov_b32_e32 v31, 0
	v_mov_b32_e32 v32, 0
	v_mov_b32_e32 v33, 0
	v_mov_b32_e32 v34, 0
	v_mov_b32_e32 v35, 0
	v_mov_b32_e32 v36, 0
	v_mov_b32_e32 v37, 0
	v_mov_b32_e32 v38, 0
	v_mov_b32_e32 v39, 0
	v_mov_b32_e32 v40, 0
	v_mov_b32_e32 v41, 0
	v_mov_b32_e32 v42, 0
	v_mov_b32_e32 v43, 0
	v_mov_b32_e32 v44, 0
	v_mov_b32_e32 v45, 0
	v_mov_b32_e32 v46, 0
	v_mov_b32_e32 v47, 0
	v_mov_b32_e32 v64, 0
	v_mov_b32_e32 v65, 0
	v_mov_b32_e32 v66, 0
	v_mov_b32_e32 v67, 0
	v_mov_b32_e32 v68, 0
	v_mov_b32_e32 v69, 0
	v_mov_b32_e32 v70, 0
	v_mov_b32_e32 v71, 0
	v_mov_b32_e32 v72, 0
	v_mov_b32_e32 v73, 0
	v_mov_b32_e32 v74, 0
	v_mov_b32_e32 v75, 0
	v_mov_b32_e32 v76, 0
	v_mov_b32_e32 v77, 0
	v_mov_b32_e32 v78, 0
	v_mov_b32_e32 v79, 0
	v_mov_b32_e32 v234, 0
	v_mov_b32_e32 v79, 0
	v_readfirstlane_b32 s36, v230
	v_readfirstlane_b32 s37, v231
	s_mov_b32 s94, 1
	s_mov_b32 s95, 1
	s_mov_b32 s33, 0
	s_lshr_b32 s50, s29, 6
	s_lshl_b32 s51, s50, 10
	s_lshl_b32 s93, s50, 8
	s_lshl_b32 s50, s50, 3
	v_lshrrev_b32_e32 v132, 3, v227
	v_add_u32_e32 v132, s50, v132
	v_bfe_u32 v133, v132, 1, 3
	v_and_b32_e32 v134, 7, v227
	v_xor_b32_e32 v134, v134, v133
	v_lshlrev_b32_e32 v132, 7, v132
	v_lshl_or_b32 v158, v134, 4, v132
	v_add_u32_e32 v159, 0x2000, v158
	v_bfe_u32 v132, v227, 2, 3
	v_add_u32_e32 v132, s50, v132
	v_lshrrev_b32_e32 v133, 5, v227
	v_and_b32_e32 v134, 3, v227
	v_lshlrev_b32_e32 v133, 6, v133
	v_lshl_or_b32 v133, v134, 4, v133
	v_lshl_or_b32 v160, v132, 7, v133
	v_add_u32_e32 v161, 0x2000, v160
	s_lshl_b32 s50, s8, 2
	v_add_u32_e32 v132, s50, v248
	v_bfe_u32 v133, v247, 1, 3
	v_xor_b32_e32 v132, v132, v133
	v_lshlrev_b32_e32 v133, 7, v247
	v_lshl_or_b32 v144, v132, 4, v133
	v_xor_b32_e32 v145, 32, v144
	v_add_u32_e32 v146, 0x3000, v249
	s_add_u32 s93, s93, 0x19800
	v_lshlrev_b32_e32 v132, 2, v247
	v_add_u32_e32 v148, s93, v132
	v_lshlrev_b32_e32 v132, 4, v248
	v_add_u32_e32 v147, s93, v132
	v_mov_b32_e32 v132, 0x19880
	v_mov_b32_e32 v133, 0
	ds_write_b32 v132, v133
	v_mov_b32_e32 v80, 0
	v_mov_b32_e32 v200, 0
	v_mov_b32_e32 v81, 0
	v_mov_b32_e32 v201, 0
	v_mov_b32_e32 v82, 0
	v_mov_b32_e32 v202, 0
	v_mov_b32_e32 v83, 0
	v_mov_b32_e32 v203, 0
	v_mov_b32_e32 v84, 0
	v_mov_b32_e32 v204, 0
	v_mov_b32_e32 v85, 0
	v_mov_b32_e32 v205, 0
	v_mov_b32_e32 v86, 0
	v_mov_b32_e32 v206, 0
	v_mov_b32_e32 v87, 0
	v_mov_b32_e32 v207, 0
	v_mov_b32_e32 v88, 0
	v_mov_b32_e32 v208, 0
	v_mov_b32_e32 v89, 0
	v_mov_b32_e32 v209, 0
	v_mov_b32_e32 v90, 0
	v_mov_b32_e32 v210, 0
	v_mov_b32_e32 v91, 0
	v_mov_b32_e32 v211, 0
	v_mov_b32_e32 v92, 0
	v_mov_b32_e32 v212, 0
	v_mov_b32_e32 v93, 0
	v_mov_b32_e32 v213, 0
	v_mov_b32_e32 v94, 0
	v_mov_b32_e32 v214, 0
	v_mov_b32_e32 v95, 0
	v_mov_b32_e32 v215, 0
	v_mov_b32_e32 v128, 0
	v_mov_b32_e32 v129, 0
	v_mov_b32_e32 v130, 0
	v_mov_b32_e32 v131, 0
	v_mov_b32_e32 v149, 0
	s_sub_u32 s36, s36, s51
	s_subb_u32 s37, s37, 0
	s_add_u32 s48, s36, 0x1d200000
	s_addc_u32 s49, s37, 0
	s_add_u32 s36, s36, 0x1c000000
	s_addc_u32 s37, s37, 0
	s_cmp_eq_u32 s8, 0
	s_cbranch_scc0 .Lat_noprioS
	s_setprio 1
